# static s_setprio 1 for waves 4-7 extended to the P3 DFT GEMM K-loop (flips deleted there too), on top of v071
# speedup vs baseline: 1.0058x; 1.0058x over previous
.LBB0_295:
	s_add_u32 s50, s50, 0x80080
	s_addc_u32 s51, s51, 0
	s_add_u32 s45, s52, 0x100
	v_mov_b32_e32 v0, 0
	s_addc_u32 s66, s53, 0
	s_mov_b32 s67, -2
	v_mov_b32_e32 v1, v0
	v_mov_b32_e32 v2, v0
	v_mov_b32_e32 v3, v0
	v_mov_b32_e32 v4, v0
	v_mov_b32_e32 v5, v0
	v_mov_b32_e32 v6, v0
	v_mov_b32_e32 v7, v0
	v_mov_b32_e32 v8, v0
	v_mov_b32_e32 v9, v0
	v_mov_b32_e32 v10, v0
	v_mov_b32_e32 v11, v0
	v_mov_b32_e32 v16, v0
	v_mov_b32_e32 v17, v0
	v_mov_b32_e32 v18, v0
	v_mov_b32_e32 v19, v0
	v_mov_b32_e32 v24, v0
	v_mov_b32_e32 v25, v0
	v_mov_b32_e32 v26, v0
	v_mov_b32_e32 v27, v0
	v_mov_b32_e32 v32, v0
	v_mov_b32_e32 v33, v0
	v_mov_b32_e32 v34, v0
	v_mov_b32_e32 v35, v0
	v_mov_b32_e32 v40, v0
	v_mov_b32_e32 v41, v0
	v_mov_b32_e32 v42, v0
	v_mov_b32_e32 v43, v0
	v_mov_b32_e32 v48, v0
	v_mov_b32_e32 v49, v0
	v_mov_b32_e32 v50, v0
	v_mov_b32_e32 v51, v0
	v_mov_b32_e32 v12, v0
	v_mov_b32_e32 v13, v0
	v_mov_b32_e32 v14, v0
	v_mov_b32_e32 v15, v0
	v_mov_b32_e32 v20, v0
	v_mov_b32_e32 v21, v0
	v_mov_b32_e32 v22, v0
	v_mov_b32_e32 v23, v0
	v_mov_b32_e32 v28, v0
	v_mov_b32_e32 v29, v0
	v_mov_b32_e32 v30, v0
	v_mov_b32_e32 v31, v0
	v_mov_b32_e32 v36, v0
	v_mov_b32_e32 v37, v0
	v_mov_b32_e32 v38, v0
	v_mov_b32_e32 v39, v0
	v_mov_b32_e32 v44, v0
	v_mov_b32_e32 v45, v0
	v_mov_b32_e32 v46, v0
	v_mov_b32_e32 v47, v0
	v_mov_b32_e32 v52, v0
	v_mov_b32_e32 v53, v0
	v_mov_b32_e32 v54, v0
	v_mov_b32_e32 v55, v0
	v_mov_b32_e32 v56, v0
	v_mov_b32_e32 v57, v0
	v_mov_b32_e32 v58, v0
	v_mov_b32_e32 v59, v0
	v_mov_b32_e32 v60, v0
	v_mov_b32_e32 v61, v0
	v_mov_b32_e32 v62, v0
	v_mov_b32_e32 v63, v0
	v_mov_b32_e32 v64, v0
	v_mov_b32_e32 v65, v0
	v_mov_b32_e32 v66, v0
	v_mov_b32_e32 v67, v0
	v_mov_b32_e32 v68, v0
	v_mov_b32_e32 v69, v0
	v_mov_b32_e32 v70, v0
	v_mov_b32_e32 v71, v0
	v_mov_b32_e32 v72, v0
	v_mov_b32_e32 v73, v0
	v_mov_b32_e32 v74, v0
	v_mov_b32_e32 v75, v0
	v_mov_b32_e32 v80, v0
	v_mov_b32_e32 v81, v0
	v_mov_b32_e32 v82, v0
	v_mov_b32_e32 v83, v0
	v_mov_b32_e32 v88, v0
	v_mov_b32_e32 v89, v0
	v_mov_b32_e32 v90, v0
	v_mov_b32_e32 v91, v0
	v_mov_b32_e32 v96, v0
	v_mov_b32_e32 v97, v0
	v_mov_b32_e32 v98, v0
	v_mov_b32_e32 v99, v0
	v_mov_b32_e32 v104, v0
	v_mov_b32_e32 v105, v0
	v_mov_b32_e32 v106, v0
	v_mov_b32_e32 v107, v0
	v_mov_b32_e32 v112, v0
	v_mov_b32_e32 v113, v0
	v_mov_b32_e32 v114, v0
	v_mov_b32_e32 v115, v0
	v_mov_b32_e32 v76, v0
	v_mov_b32_e32 v77, v0
	v_mov_b32_e32 v78, v0
	v_mov_b32_e32 v79, v0
	v_mov_b32_e32 v84, v0
	v_mov_b32_e32 v85, v0
	v_mov_b32_e32 v86, v0
	v_mov_b32_e32 v87, v0
	v_mov_b32_e32 v92, v0
	v_mov_b32_e32 v93, v0
	v_mov_b32_e32 v94, v0
	v_mov_b32_e32 v95, v0
	v_mov_b32_e32 v100, v0
	v_mov_b32_e32 v101, v0
	v_mov_b32_e32 v102, v0
	v_mov_b32_e32 v103, v0
	v_mov_b32_e32 v108, v0
	v_mov_b32_e32 v109, v0
	v_mov_b32_e32 v110, v0
	v_mov_b32_e32 v111, v0
	v_mov_b32_e32 v116, v0
	v_mov_b32_e32 v117, v0
	v_mov_b32_e32 v118, v0
	v_mov_b32_e32 v119, v0
	v_mov_b32_e32 v120, v0
	v_mov_b32_e32 v121, v0
	v_mov_b32_e32 v122, v0
	v_mov_b32_e32 v123, v0
	v_mov_b32_e32 v124, v0
	v_mov_b32_e32 v125, v0
	v_mov_b32_e32 v126, v0
	v_mov_b32_e32 v127, v0
	v_readlane_b32 s52, v254, 6
	s_nop 3
	s_cmp_ge_u32 s52, 0x100
	s_cbranch_scc0 .Lsprio_p3a
	s_setprio 1
.Lsprio_p3a:
.LBB0_296:
	ds_read_b128 v[140:143], v146
	ds_read_b128 v[152:155], v146 offset:1024
	ds_read_b128 v[156:159], v146 offset:2048
	ds_read_b128 v[160:163], v146 offset:3072
	ds_read_b128 v[164:167], v147
	ds_read_b128 v[168:171], v147 offset:1024
	ds_read_b128 v[172:175], v147 offset:2048
	ds_read_b128 v[176:179], v147 offset:3072
	s_add_u32 s21, s50, 0xfff80080
	s_addc_u32 s52, s51, -1
	s_cmp_eq_u32 s67, 12
	s_cselect_b32 s55, s17, s52
	s_cselect_b32 s54, s16, s21
	s_cselect_b32 s53, s23, s66
	s_cselect_b32 s52, s22, s45
	s_mov_b32 m0, s94
	v_lshl_add_u64 v[184:185], s[50:51], 0, v[136:137]
	ds_read_b128 v[180:183], v148
	ds_read_b128 v[188:191], v148 offset:1024
	ds_read_b128 v[192:195], v148 offset:2048
	ds_read_b128 v[196:199], v148 offset:3072
	ds_read_b128 v[200:203], v148 offset:4096
	ds_read_b128 v[204:207], v148 offset:5120
	ds_read_b128 v[208:211], v148 offset:6144
	ds_read_b128 v[212:215], v148 offset:7168
	global_load_lds_dwordx4 v[184:185], off
	v_lshl_add_u64 v[184:185], s[50:51], 0, v[138:139]
	s_mov_b32 m0, s95
	s_nop 0
	global_load_lds_dwordx4 v[184:185], off
	s_waitcnt vmcnt(8)
	s_waitcnt lgkmcnt(0)
	s_barrier
	s_waitcnt lgkmcnt(0)
	v_mfma_f32_16x16x32_bf16 v[124:127], v[140:143], v[180:183], v[124:127]
	v_mfma_f32_16x16x32_bf16 v[120:123], v[156:159], v[180:183], v[120:123]
	v_mfma_f32_16x16x32_bf16 v[116:119], v[140:143], v[192:195], v[116:119]
	v_mfma_f32_16x16x32_bf16 v[108:111], v[156:159], v[192:195], v[108:111]
	v_mfma_f32_16x16x32_bf16 v[100:103], v[140:143], v[200:203], v[100:103]
	v_mfma_f32_16x16x32_bf16 v[92:95], v[156:159], v[200:203], v[92:95]
	v_mfma_f32_16x16x32_bf16 v[84:87], v[140:143], v[208:211], v[84:87]
	v_mfma_f32_16x16x32_bf16 v[76:79], v[156:159], v[208:211], v[76:79]
	v_mfma_f32_16x16x32_bf16 v[124:127], v[152:155], v[188:191], v[124:127]
	v_mfma_f32_16x16x32_bf16 v[120:123], v[160:163], v[188:191], v[120:123]
	v_mfma_f32_16x16x32_bf16 v[116:119], v[152:155], v[196:199], v[116:119]
	v_mfma_f32_16x16x32_bf16 v[108:111], v[160:163], v[196:199], v[108:111]
	v_mfma_f32_16x16x32_bf16 v[100:103], v[152:155], v[204:207], v[100:103]
	v_mfma_f32_16x16x32_bf16 v[92:95], v[160:163], v[204:207], v[92:95]
	v_mfma_f32_16x16x32_bf16 v[84:87], v[152:155], v[212:215], v[84:87]
	v_mfma_f32_16x16x32_bf16 v[76:79], v[160:163], v[212:215], v[76:79]
	v_mfma_f32_16x16x32_bf16 v[112:115], v[164:167], v[180:183], v[112:115]
	v_mfma_f32_16x16x32_bf16 v[104:107], v[172:175], v[180:183], v[104:107]
	v_mfma_f32_16x16x32_bf16 v[96:99], v[164:167], v[192:195], v[96:99]
	v_mfma_f32_16x16x32_bf16 v[88:91], v[172:175], v[192:195], v[88:91]
	v_mfma_f32_16x16x32_bf16 v[80:83], v[164:167], v[200:203], v[80:83]
	v_mfma_f32_16x16x32_bf16 v[72:75], v[172:175], v[200:203], v[72:75]
	v_mfma_f32_16x16x32_bf16 v[68:71], v[164:167], v[208:211], v[68:71]
	v_mfma_f32_16x16x32_bf16 v[64:67], v[172:175], v[208:211], v[64:67]
	v_mfma_f32_16x16x32_bf16 v[112:115], v[168:171], v[188:191], v[112:115]
	v_mfma_f32_16x16x32_bf16 v[104:107], v[176:179], v[188:191], v[104:107]
	v_mfma_f32_16x16x32_bf16 v[96:99], v[168:171], v[196:199], v[96:99]
	v_mfma_f32_16x16x32_bf16 v[88:91], v[176:179], v[196:199], v[88:91]
	v_mfma_f32_16x16x32_bf16 v[80:83], v[168:171], v[204:207], v[80:83]
	v_mfma_f32_16x16x32_bf16 v[72:75], v[176:179], v[204:207], v[72:75]
	v_mfma_f32_16x16x32_bf16 v[68:71], v[168:171], v[212:215], v[68:71]
	v_mfma_f32_16x16x32_bf16 v[64:67], v[176:179], v[212:215], v[64:67]
	s_barrier
	s_mov_b32 m0, s96
	v_lshl_add_u64 v[184:185], s[52:53], 0, v[132:133]
	s_add_u32 s74, s52, 0x80000
	ds_read_b128 v[180:183], v148 offset:16384
	ds_read_b128 v[188:191], v148 offset:17408
	ds_read_b128 v[192:195], v148 offset:18432
	ds_read_b128 v[196:199], v148 offset:19456
	ds_read_b128 v[200:203], v148 offset:20480
	ds_read_b128 v[204:207], v148 offset:21504
	ds_read_b128 v[208:211], v148 offset:22528
	ds_read_b128 v[212:215], v148 offset:23552
	global_load_lds_dwordx4 v[184:185], off
	v_lshl_add_u64 v[216:217], s[52:53], 0, v[128:129]
	s_mov_b32 m0, s97
	s_addc_u32 s75, s53, 0
	global_load_lds_dwordx4 v[216:217], off
	v_lshl_add_u64 v[218:219], s[74:75], 0, v[132:133]
	s_mov_b32 m0, s91
	v_lshl_add_u64 v[220:221], s[54:55], 0, v[130:131]
	global_load_lds_dwordx4 v[218:219], off
	v_lshl_add_u64 v[218:219], s[74:75], 0, v[128:129]
	s_mov_b32 m0, s26
	s_nop 0
	global_load_lds_dwordx4 v[218:219], off
	v_lshl_add_u64 v[218:219], s[54:55], 0, v[134:135]
	s_mov_b32 m0, s33
	s_nop 0
	global_load_lds_dwordx4 v[218:219], off
	s_mov_b32 m0, s88
	s_nop 0
	global_load_lds_dwordx4 v[220:221], off
	s_waitcnt vmcnt(8)
	s_waitcnt lgkmcnt(0)
	s_barrier
	s_waitcnt lgkmcnt(0)
	v_mfma_f32_16x16x32_bf16 v[60:63], v[140:143], v[180:183], v[60:63]
	v_mfma_f32_16x16x32_bf16 v[56:59], v[156:159], v[180:183], v[56:59]
	v_mfma_f32_16x16x32_bf16 v[52:55], v[140:143], v[192:195], v[52:55]
	v_mfma_f32_16x16x32_bf16 v[44:47], v[156:159], v[192:195], v[44:47]
	v_mfma_f32_16x16x32_bf16 v[36:39], v[140:143], v[200:203], v[36:39]
	v_mfma_f32_16x16x32_bf16 v[28:31], v[156:159], v[200:203], v[28:31]
	v_mfma_f32_16x16x32_bf16 v[20:23], v[140:143], v[208:211], v[20:23]
	v_mfma_f32_16x16x32_bf16 v[12:15], v[156:159], v[208:211], v[12:15]
	v_mfma_f32_16x16x32_bf16 v[60:63], v[152:155], v[188:191], v[60:63]
	v_mfma_f32_16x16x32_bf16 v[56:59], v[160:163], v[188:191], v[56:59]
	v_mfma_f32_16x16x32_bf16 v[52:55], v[152:155], v[196:199], v[52:55]
	v_mfma_f32_16x16x32_bf16 v[44:47], v[160:163], v[196:199], v[44:47]
	v_mfma_f32_16x16x32_bf16 v[36:39], v[152:155], v[204:207], v[36:39]
	v_mfma_f32_16x16x32_bf16 v[28:31], v[160:163], v[204:207], v[28:31]
	v_mfma_f32_16x16x32_bf16 v[20:23], v[152:155], v[212:215], v[20:23]
	v_mfma_f32_16x16x32_bf16 v[12:15], v[160:163], v[212:215], v[12:15]
	v_mfma_f32_16x16x32_bf16 v[48:51], v[164:167], v[180:183], v[48:51]
	v_mfma_f32_16x16x32_bf16 v[40:43], v[172:175], v[180:183], v[40:43]
	v_mfma_f32_16x16x32_bf16 v[32:35], v[164:167], v[192:195], v[32:35]
	v_mfma_f32_16x16x32_bf16 v[24:27], v[172:175], v[192:195], v[24:27]
	v_mfma_f32_16x16x32_bf16 v[16:19], v[164:167], v[200:203], v[16:19]
	v_mfma_f32_16x16x32_bf16 v[8:11], v[172:175], v[200:203], v[8:11]
	v_mfma_f32_16x16x32_bf16 v[4:7], v[164:167], v[208:211], v[4:7]
	v_mfma_f32_16x16x32_bf16 v[0:3], v[172:175], v[208:211], v[0:3]
	v_mfma_f32_16x16x32_bf16 v[48:51], v[168:171], v[188:191], v[48:51]
	v_mfma_f32_16x16x32_bf16 v[40:43], v[176:179], v[188:191], v[40:43]
	v_mfma_f32_16x16x32_bf16 v[32:35], v[168:171], v[196:199], v[32:35]
	v_mfma_f32_16x16x32_bf16 v[24:27], v[176:179], v[196:199], v[24:27]
	v_mfma_f32_16x16x32_bf16 v[16:19], v[168:171], v[204:207], v[16:19]
	v_mfma_f32_16x16x32_bf16 v[8:11], v[176:179], v[204:207], v[8:11]
	v_mfma_f32_16x16x32_bf16 v[4:7], v[168:171], v[212:215], v[4:7]
	v_mfma_f32_16x16x32_bf16 v[0:3], v[176:179], v[212:215], v[0:3]
	s_barrier
	ds_read_b128 v[140:143], v149
	ds_read_b128 v[152:155], v149 offset:1024
	ds_read_b128 v[156:159], v149 offset:2048
	ds_read_b128 v[160:163], v149 offset:3072
	ds_read_b128 v[164:167], v150
	ds_read_b128 v[168:171], v150 offset:1024
	ds_read_b128 v[172:175], v150 offset:2048
	ds_read_b128 v[176:179], v150 offset:3072
	s_add_u32 s54, s54, 0x80000
	s_addc_u32 s55, s55, 0
	s_mov_b32 m0, s89
	v_lshl_add_u64 v[222:223], s[54:55], 0, v[134:135]
	ds_read_b128 v[180:183], v148 offset:32768
	ds_read_b128 v[188:191], v148 offset:33792
	ds_read_b128 v[192:195], v148 offset:34816
	ds_read_b128 v[196:199], v148 offset:35840
	ds_read_b128 v[200:203], v148 offset:36864
	ds_read_b128 v[204:207], v148 offset:37888
	ds_read_b128 v[208:211], v148 offset:38912
	ds_read_b128 v[212:215], v148 offset:39936
	global_load_lds_dwordx4 v[222:223], off
	v_lshl_add_u64 v[222:223], s[54:55], 0, v[130:131]
	s_mov_b32 m0, s90
	s_nop 0
	global_load_lds_dwordx4 v[222:223], off
	s_waitcnt vmcnt(8)
	s_waitcnt lgkmcnt(0)
	s_barrier
	s_waitcnt lgkmcnt(0)
	v_mfma_f32_16x16x32_bf16 v[124:127], v[140:143], v[180:183], v[124:127]
	v_mfma_f32_16x16x32_bf16 v[120:123], v[156:159], v[180:183], v[120:123]
	v_mfma_f32_16x16x32_bf16 v[116:119], v[140:143], v[192:195], v[116:119]
	v_mfma_f32_16x16x32_bf16 v[108:111], v[156:159], v[192:195], v[108:111]
	v_mfma_f32_16x16x32_bf16 v[100:103], v[140:143], v[200:203], v[100:103]
	v_mfma_f32_16x16x32_bf16 v[92:95], v[156:159], v[200:203], v[92:95]
	v_mfma_f32_16x16x32_bf16 v[84:87], v[140:143], v[208:211], v[84:87]
	v_mfma_f32_16x16x32_bf16 v[76:79], v[156:159], v[208:211], v[76:79]
	v_mfma_f32_16x16x32_bf16 v[124:127], v[152:155], v[188:191], v[124:127]
	v_mfma_f32_16x16x32_bf16 v[120:123], v[160:163], v[188:191], v[120:123]
	v_mfma_f32_16x16x32_bf16 v[116:119], v[152:155], v[196:199], v[116:119]
	v_mfma_f32_16x16x32_bf16 v[108:111], v[160:163], v[196:199], v[108:111]
	v_mfma_f32_16x16x32_bf16 v[100:103], v[152:155], v[204:207], v[100:103]
	v_mfma_f32_16x16x32_bf16 v[92:95], v[160:163], v[204:207], v[92:95]
	v_mfma_f32_16x16x32_bf16 v[84:87], v[152:155], v[212:215], v[84:87]
	v_mfma_f32_16x16x32_bf16 v[76:79], v[160:163], v[212:215], v[76:79]
	v_mfma_f32_16x16x32_bf16 v[112:115], v[164:167], v[180:183], v[112:115]
	v_mfma_f32_16x16x32_bf16 v[104:107], v[172:175], v[180:183], v[104:107]
	v_mfma_f32_16x16x32_bf16 v[96:99], v[164:167], v[192:195], v[96:99]
	v_mfma_f32_16x16x32_bf16 v[88:91], v[172:175], v[192:195], v[88:91]
	v_mfma_f32_16x16x32_bf16 v[80:83], v[164:167], v[200:203], v[80:83]
	v_mfma_f32_16x16x32_bf16 v[72:75], v[172:175], v[200:203], v[72:75]
	v_mfma_f32_16x16x32_bf16 v[68:71], v[164:167], v[208:211], v[68:71]
	v_mfma_f32_16x16x32_bf16 v[64:67], v[172:175], v[208:211], v[64:67]
	v_mfma_f32_16x16x32_bf16 v[112:115], v[168:171], v[188:191], v[112:115]
	v_mfma_f32_16x16x32_bf16 v[104:107], v[176:179], v[188:191], v[104:107]
	v_mfma_f32_16x16x32_bf16 v[96:99], v[168:171], v[196:199], v[96:99]
	v_mfma_f32_16x16x32_bf16 v[88:91], v[176:179], v[196:199], v[88:91]
	v_mfma_f32_16x16x32_bf16 v[80:83], v[168:171], v[204:207], v[80:83]
	v_mfma_f32_16x16x32_bf16 v[72:75], v[176:179], v[204:207], v[72:75]
	v_mfma_f32_16x16x32_bf16 v[68:71], v[168:171], v[212:215], v[68:71]
	v_mfma_f32_16x16x32_bf16 v[64:67], v[176:179], v[212:215], v[64:67]
	s_barrier
	s_mov_b32 m0, s27
	v_lshl_add_u64 v[184:185], v[184:185], 0, s[14:15]
	s_add_u32 s52, s52, 0x80080
	ds_read_b128 v[180:183], v148 offset:49152
	ds_read_b128 v[188:191], v148 offset:50176
	ds_read_b128 v[192:195], v148 offset:51200
	ds_read_b128 v[196:199], v148 offset:52224
	ds_read_b128 v[200:203], v148 offset:53248
	ds_read_b128 v[204:207], v148 offset:54272
	ds_read_b128 v[208:211], v148 offset:55296
	ds_read_b128 v[212:215], v148 offset:56320
	global_load_lds_dwordx4 v[184:185], off
	v_lshl_add_u64 v[184:185], v[216:217], 0, s[14:15]
	s_mov_b32 m0, s34
	s_addc_u32 s53, s53, 0
	global_load_lds_dwordx4 v[184:185], off
	v_lshl_add_u64 v[184:185], s[52:53], 0, v[132:133]
	s_mov_b32 m0, s35
	s_nop 0
	global_load_lds_dwordx4 v[184:185], off
	v_lshl_add_u64 v[184:185], s[52:53], 0, v[128:129]
	s_mov_b32 m0, s28
	s_nop 0
	global_load_lds_dwordx4 v[184:185], off
	v_lshl_add_u64 v[184:185], v[218:219], 0, s[14:15]
	s_mov_b32 m0, s92
	s_nop 0
	global_load_lds_dwordx4 v[184:185], off
	v_lshl_add_u64 v[184:185], v[220:221], 0, s[14:15]
	s_mov_b32 m0, s93
	s_nop 0
	global_load_lds_dwordx4 v[184:185], off
	s_waitcnt vmcnt(8)
	s_waitcnt lgkmcnt(0)
	s_barrier
	s_waitcnt lgkmcnt(0)
	v_mfma_f32_16x16x32_bf16 v[60:63], v[140:143], v[180:183], v[60:63]
	v_mfma_f32_16x16x32_bf16 v[56:59], v[156:159], v[180:183], v[56:59]
	v_mfma_f32_16x16x32_bf16 v[52:55], v[140:143], v[192:195], v[52:55]
	v_mfma_f32_16x16x32_bf16 v[44:47], v[156:159], v[192:195], v[44:47]
	v_mfma_f32_16x16x32_bf16 v[36:39], v[140:143], v[200:203], v[36:39]
	v_mfma_f32_16x16x32_bf16 v[28:31], v[156:159], v[200:203], v[28:31]
	v_mfma_f32_16x16x32_bf16 v[20:23], v[140:143], v[208:211], v[20:23]
	v_mfma_f32_16x16x32_bf16 v[12:15], v[156:159], v[208:211], v[12:15]
	v_mfma_f32_16x16x32_bf16 v[60:63], v[152:155], v[188:191], v[60:63]
	v_mfma_f32_16x16x32_bf16 v[56:59], v[160:163], v[188:191], v[56:59]
	v_mfma_f32_16x16x32_bf16 v[52:55], v[152:155], v[196:199], v[52:55]
	v_mfma_f32_16x16x32_bf16 v[44:47], v[160:163], v[196:199], v[44:47]
	v_mfma_f32_16x16x32_bf16 v[36:39], v[152:155], v[204:207], v[36:39]
	v_mfma_f32_16x16x32_bf16 v[28:31], v[160:163], v[204:207], v[28:31]
	v_mfma_f32_16x16x32_bf16 v[20:23], v[152:155], v[212:215], v[20:23]
	v_mfma_f32_16x16x32_bf16 v[12:15], v[160:163], v[212:215], v[12:15]
	v_mfma_f32_16x16x32_bf16 v[48:51], v[164:167], v[180:183], v[48:51]
	v_mfma_f32_16x16x32_bf16 v[40:43], v[172:175], v[180:183], v[40:43]
	v_mfma_f32_16x16x32_bf16 v[32:35], v[164:167], v[192:195], v[32:35]
	v_mfma_f32_16x16x32_bf16 v[24:27], v[172:175], v[192:195], v[24:27]
	v_mfma_f32_16x16x32_bf16 v[16:19], v[164:167], v[200:203], v[16:19]
	v_mfma_f32_16x16x32_bf16 v[8:11], v[172:175], v[200:203], v[8:11]
	v_mfma_f32_16x16x32_bf16 v[4:7], v[164:167], v[208:211], v[4:7]
	v_mfma_f32_16x16x32_bf16 v[0:3], v[172:175], v[208:211], v[0:3]
	v_mfma_f32_16x16x32_bf16 v[48:51], v[168:171], v[188:191], v[48:51]
	v_mfma_f32_16x16x32_bf16 v[40:43], v[176:179], v[188:191], v[40:43]
	v_mfma_f32_16x16x32_bf16 v[32:35], v[168:171], v[196:199], v[32:35]
	v_mfma_f32_16x16x32_bf16 v[24:27], v[176:179], v[196:199], v[24:27]
	v_mfma_f32_16x16x32_bf16 v[16:19], v[168:171], v[204:207], v[16:19]
	v_mfma_f32_16x16x32_bf16 v[8:11], v[176:179], v[204:207], v[8:11]
	v_mfma_f32_16x16x32_bf16 v[4:7], v[168:171], v[212:215], v[4:7]
	v_mfma_f32_16x16x32_bf16 v[0:3], v[176:179], v[212:215], v[0:3]
	s_barrier
	s_add_i32 s67, s67, 2
	s_add_u32 s50, s50, 0x100
	s_addc_u32 s51, s51, 0
	s_add_u32 s45, s45, 0x100
	s_addc_u32 s66, s66, 0
	s_cmp_gt_u32 s67, 13
	s_cbranch_scc0 .LBB0_296
	s_setprio 0
	s_and_b64 vcc, exec, s[78:79]
	s_cbranch_vccz .LBB0_299
	s_barrier
